# meta-token tiles: loads of all unrolled k-steps issued together with counted vmcnt (5 sites), on top of hand-off + DMA-first + epilogue de-serialisation
# baseline (speedup 1.0000x reference)
; #define LAS __attribute__((address_space(3)))
; template <int NACC> __device__ __forceinline__ void meta_tile(const bf16* A, int K, const bf16* B0, const bf16* B1, const bf16* B2, LAS float* red, int wid, int lane, f32x4 (&out)[NACC]) {
;     const int ks = K >> 3, r = lane & 15, kq = (lane >> 4) * 8;
;     const size_t off = (size_t)r * K + wid * ks + kq;
;     const bf16* ap = A + off; const bf16* bp[3] = {B0 + off, B1 + off, B2 + off};
;     f32x4 acc[NACC];
; #pragma unroll
;     for (int j = 0; j < NACC; ++j) acc[j] = (f32x4){0.f, 0.f, 0.f, 0.f};
; #pragma unroll 8
;     for (int k = 0; k < ks; k += 32) {
;         const bf16x8 a = *(const bf16x8*)(ap + k);
; #pragma unroll
;         for (int j = 0; j < NACC; ++j) { const bf16x8 b = *(const bf16x8*)(bp[j] + k); acc[j] = __builtin_amdgcn_mfma_f32_16x16x32_bf16(b, a, acc[j], 0, 0, 0); }
;     }
;     LAS f32x4* R = (LAS f32x4*)red;
; #pragma unroll
;     for (int j = 0; j < NACC; ++j) { R[(wid * NACC + j) * 64 + lane] = acc[j]; out[j] = acc[j]; }
;     __syncthreads();
;     if (wid == 0) {
; #pragma unroll
;         for (int j = 0; j < NACC; ++j) { f32x4 s = R[j * 64 + lane];
; #pragma unroll
;             for (int w = 1; w < 8; ++w) s += R[(w * NACC + j) * 64 + lane];
;             out[j] = s; }
; __global__ void __launch_bounds__(512, 2) fwd_mega(Args args) {
;     ...
;                     const bool isk = pt < 8; const int p8 = pt & 7, mwc = p8 >> 1, mh = p8 & 1;
;                     const bf16* b0 = W5 + (size_t)((isk ? 2048 : 2304) + 32 * mwc + 16 * mh) * DM;
;                     meta_tile<2>(XNm, DM, b0, b0 + (size_t)128 * DM, b0, red, wid, lane, r2);
.LBB0_199:
	s_cmp_gt_i32 s20, 7
	s_cselect_b64 s[10:11], -1, 0
	s_bfe_u32 s14, s20, 0x20001
	s_cmp_lt_i32 s20, 8
	s_movk_i32 s0, 0x800
	s_cselect_b32 s0, s0, 0x900
	s_lshl_b32 s1, s14, 5
	s_or_b32 s1, s1, s0
	s_and_b32 s0, s12, 16
	s_or_b32 s1, s1, s0
	s_lshl_b32 s1, s1, 12
	s_add_u32 s2, s60, s1
	s_addc_u32 s3, s61, 0
	v_lshl_add_u64 v[32:33], v[8:9], 1, s[2:3]
	v_add_co_u32_e32 v26, vcc, s89, v32
	global_load_dwordx4 v[44:47], v[10:11], off
	global_load_dwordx4 v[48:51], v[32:33], off
	v_addc_co_u32_e32 v27, vcc, 0, v33, vcc
	global_load_dwordx4 v[52:55], v[26:27], off
	s_mov_b64 s[2:3], 0x80000
	v_lshl_add_u64 v[40:41], v[32:33], 0, s[2:3]
	s_andn2_b64 vcc, exec, s[16:17]
	global_load_dwordx4 v[56:59], v[10:11], off offset:64
	global_load_dwordx4 v[60:63], v[32:33], off offset:64
	global_load_dwordx4 v[64:67], v[40:41], off offset:64
	global_load_dwordx4 v[68:71], v[10:11], off offset:128
	global_load_dwordx4 v[72:75], v[32:33], off offset:128
	global_load_dwordx4 v[76:79], v[40:41], off offset:128
	global_load_dwordx4 v[80:83], v[10:11], off offset:192
	global_load_dwordx4 v[84:87], v[32:33], off offset:192
	global_load_dwordx4 v[88:91], v[40:41], off offset:192
	s_waitcnt vmcnt(10)
	v_mfma_f32_16x16x32_bf16 v[4:7], v[48:51], v[44:47], 0
	s_waitcnt vmcnt(9)
	v_mfma_f32_16x16x32_bf16 v[0:3], v[52:55], v[44:47], 0
	s_waitcnt vmcnt(7)
	v_mfma_f32_16x16x32_bf16 v[4:7], v[60:63], v[56:59], v[4:7]
	s_waitcnt vmcnt(6)
	v_mfma_f32_16x16x32_bf16 v[0:3], v[64:67], v[56:59], v[0:3]
	s_waitcnt vmcnt(4)
	v_mfma_f32_16x16x32_bf16 v[4:7], v[72:75], v[68:71], v[4:7]
	s_waitcnt vmcnt(3)
	v_mfma_f32_16x16x32_bf16 v[0:3], v[76:79], v[68:71], v[0:3]
	s_waitcnt vmcnt(1)
	v_mfma_f32_16x16x32_bf16 v[4:7], v[84:87], v[80:83], v[4:7]
	s_waitcnt vmcnt(0)
	v_mfma_f32_16x16x32_bf16 v[0:3], v[88:91], v[80:83], v[0:3]
	global_load_dwordx4 v[44:47], v[10:11], off offset:256
	global_load_dwordx4 v[48:51], v[32:33], off offset:256
	global_load_dwordx4 v[52:55], v[40:41], off offset:256
	global_load_dwordx4 v[56:59], v[10:11], off offset:320
	global_load_dwordx4 v[60:63], v[32:33], off offset:320
	global_load_dwordx4 v[64:67], v[40:41], off offset:320
	global_load_dwordx4 v[68:71], v[10:11], off offset:384
	global_load_dwordx4 v[72:75], v[32:33], off offset:384
	global_load_dwordx4 v[76:79], v[40:41], off offset:384
	global_load_dwordx4 v[80:83], v[10:11], off offset:448
	global_load_dwordx4 v[84:87], v[32:33], off offset:448
	global_load_dwordx4 v[88:91], v[40:41], off offset:448
	s_waitcnt vmcnt(10)
	v_mfma_f32_16x16x32_bf16 v[4:7], v[48:51], v[44:47], v[4:7]
	s_waitcnt vmcnt(9)
	v_mfma_f32_16x16x32_bf16 v[0:3], v[52:55], v[44:47], v[0:3]
	s_waitcnt vmcnt(7)
	v_mfma_f32_16x16x32_bf16 v[4:7], v[60:63], v[56:59], v[4:7]
	s_waitcnt vmcnt(6)
	v_mfma_f32_16x16x32_bf16 v[0:3], v[64:67], v[56:59], v[0:3]
	s_waitcnt vmcnt(4)
	v_mfma_f32_16x16x32_bf16 v[4:7], v[72:75], v[68:71], v[4:7]
	s_waitcnt vmcnt(3)
	v_mfma_f32_16x16x32_bf16 v[26:29], v[76:79], v[68:71], v[0:3]
	s_waitcnt vmcnt(1)
	v_mfma_f32_16x16x32_bf16 v[0:3], v[84:87], v[80:83], v[4:7]
	s_waitcnt vmcnt(0)
	v_mfma_f32_16x16x32_bf16 v[4:7], v[88:91], v[80:83], v[26:29]
	s_nop 7
	s_nop 2
	v_add_u32_e32 v26, s21, v31
	ds_write_b128 v26, v[0:3]
	s_nop 2
	ds_write_b128 v26, v[4:7] offset:1024
	v_cndmask_b32_e64 v26, 0, 1, s[16:17]
	v_cmp_ne_u32_e64 s[2:3], 1, v26
	s_waitcnt lgkmcnt(0)
	s_barrier
	s_cbranch_vccnz .LBB0_201
	ds_read_b128 v[0:3], v31
	ds_read_b128 v[4:7], v31 offset:2048
	s_waitcnt lgkmcnt(0)
	v_pk_add_f32 v[6:7], v[2:3], v[6:7]
	v_pk_add_f32 v[4:5], v[0:1], v[4:5]
	ds_read_b128 v[0:3], v31 offset:4096
	s_waitcnt lgkmcnt(0)
	v_pk_add_f32 v[6:7], v[6:7], v[2:3]
	v_pk_add_f32 v[4:5], v[4:5], v[0:1]
	ds_read_b128 v[0:3], v31 offset:6144
	s_waitcnt lgkmcnt(0)
	v_pk_add_f32 v[6:7], v[6:7], v[2:3]
	v_pk_add_f32 v[4:5], v[4:5], v[0:1]
	ds_read_b128 v[0:3], v31 offset:8192
	s_waitcnt lgkmcnt(0)
	v_pk_add_f32 v[6:7], v[6:7], v[2:3]
	v_pk_add_f32 v[4:5], v[4:5], v[0:1]
	ds_read_b128 v[0:3], v31 offset:10240
	s_waitcnt lgkmcnt(0)
	v_pk_add_f32 v[6:7], v[6:7], v[2:3]
	v_pk_add_f32 v[4:5], v[4:5], v[0:1]
	ds_read_b128 v[0:3], v31 offset:12288
	s_waitcnt lgkmcnt(0)
	v_pk_add_f32 v[6:7], v[6:7], v[2:3]
	v_pk_add_f32 v[4:5], v[4:5], v[0:1]
	ds_read_b128 v[0:3], v31 offset:14336
	s_waitcnt lgkmcnt(0)
	v_pk_add_f32 v[2:3], v[6:7], v[2:3]
	v_pk_add_f32 v[0:1], v[4:5], v[0:1]
	ds_read_b128 v[4:7], v31 offset:1024
	ds_read_b128 v[26:29], v31 offset:3072
	s_waitcnt lgkmcnt(0)
	v_pk_add_f32 v[28:29], v[6:7], v[28:29]
	v_pk_add_f32 v[26:27], v[4:5], v[26:27]
	ds_read_b128 v[4:7], v31 offset:5120
	s_waitcnt lgkmcnt(0)
	v_pk_add_f32 v[28:29], v[28:29], v[6:7]
	v_pk_add_f32 v[26:27], v[26:27], v[4:5]
	ds_read_b128 v[4:7], v31 offset:7168
	s_waitcnt lgkmcnt(0)
	v_pk_add_f32 v[28:29], v[28:29], v[6:7]
	v_pk_add_f32 v[26:27], v[26:27], v[4:5]
	ds_read_b128 v[4:7], v31 offset:9216
	s_waitcnt lgkmcnt(0)
	v_pk_add_f32 v[28:29], v[28:29], v[6:7]
	v_pk_add_f32 v[26:27], v[26:27], v[4:5]
	ds_read_b128 v[4:7], v31 offset:11264
	s_waitcnt lgkmcnt(0)
	v_pk_add_f32 v[28:29], v[28:29], v[6:7]
	v_pk_add_f32 v[26:27], v[26:27], v[4:5]
	ds_read_b128 v[4:7], v31 offset:13312
	s_waitcnt lgkmcnt(0)
	v_pk_add_f32 v[28:29], v[28:29], v[6:7]
	v_pk_add_f32 v[26:27], v[26:27], v[4:5]
	ds_read_b128 v[4:7], v31 offset:15360
	s_waitcnt lgkmcnt(0)
	v_pk_add_f32 v[6:7], v[28:29], v[6:7]
	v_pk_add_f32 v[4:5], v[26:27], v[4:5]

; #define LAS __attribute__((address_space(3)))
; template <int NACC> __device__ __forceinline__ void meta_tile(const bf16* A, int K, const bf16* B0, const bf16* B1, const bf16* B2, LAS float* red, int wid, int lane, f32x4 (&out)[NACC]) {
;     const int ks = K >> 3, r = lane & 15, kq = (lane >> 4) * 8;
;     const size_t off = (size_t)r * K + wid * ks + kq;
;     const bf16* ap = A + off; const bf16* bp[3] = {B0 + off, B1 + off, B2 + off};
;     f32x4 acc[NACC];
; #pragma unroll
;     for (int j = 0; j < NACC; ++j) acc[j] = (f32x4){0.f, 0.f, 0.f, 0.f};
; #pragma unroll 8
;     for (int k = 0; k < ks; k += 32) {
;         const bf16x8 a = *(const bf16x8*)(ap + k);
; #pragma unroll
;         for (int j = 0; j < NACC; ++j) { const bf16x8 b = *(const bf16x8*)(bp[j] + k); acc[j] = __builtin_amdgcn_mfma_f32_16x16x32_bf16(b, a, acc[j], 0, 0, 0); }
;     }
;     LAS f32x4* R = (LAS f32x4*)red;
; #pragma unroll
;     for (int j = 0; j < NACC; ++j) { R[(wid * NACC + j) * 64 + lane] = acc[j]; out[j] = acc[j]; }
; __global__ void __launch_bounds__(512, 2) fwd_mega(Args args) {
;     ...
;                     const bf16* bc = W1 + (size_t)(((ch0 >> 7) << 8) + (ch0 & 127)) * DM;
;                     const int lcb = ch0 & 255, pb = 128 * ((lcb >> 5) & 1) + 32 * (lcb >> 6) + (lcb & 31);
;                     meta_tile<3>(XNm, DM, bc, bc + (size_t)128 * DM, W1 + (size_t)(4096 + (ch0 & ~255) + pb) * DM, red, wid, lane, r3);
.LBB0_432:
	s_and_b32 s0, s15, 0xffffff00
	s_and_b32 s1, s6, 0x70
	s_or_b32 s0, s0, s1
	s_ashr_i32 s1, s0, 31
	s_lshl_b64 s[0:1], s[0:1], 12
	s_add_u32 s0, s4, s0
	s_addc_u32 s1, s5, s1
	s_and_b32 s2, s16, 0x80
	s_lshr_b32 s3, s6, 1
	s_and_b32 s7, s6, 0xffffff10
	s_and_b32 s3, s3, 0x60
	s_or_b32 s2, s7, s2
	s_or_b32 s2, s2, s3
	s_addk_i32 s2, 0x1000
	s_ashr_i32 s3, s2, 31
	v_lshl_add_u64 v[10:11], v[12:13], 1, s[0:1]
	s_lshl_b64 s[2:3], s[2:3], 12
	v_add_co_u32_e32 v22, vcc, s89, v10
	v_lshl_add_u64 v[8:9], v[14:15], 0, s[2:3]
	s_nop 0
	v_addc_co_u32_e32 v23, vcc, 0, v11, vcc
	global_load_dwordx4 v[36:39], v[16:17], off
	global_load_dwordx4 v[40:43], v[10:11], off
	global_load_dwordx4 v[44:47], v[8:9], off
	s_mov_b64 s[0:1], 0x80000
	global_load_dwordx4 v[48:51], v[22:23], off
	v_lshl_add_u64 v[34:35], v[10:11], 0, s[0:1]
	v_add_u32_e32 v21, s14, v20
	s_andn2_b64 vcc, exec, s[12:13]
	global_load_dwordx4 v[52:55], v[16:17], off offset:64
	global_load_dwordx4 v[56:59], v[10:11], off offset:64
	global_load_dwordx4 v[60:63], v[34:35], off offset:64
	global_load_dwordx4 v[64:67], v[8:9], off offset:64
	global_load_dwordx4 v[68:71], v[16:17], off offset:128
	global_load_dwordx4 v[72:75], v[10:11], off offset:128
	global_load_dwordx4 v[76:79], v[34:35], off offset:128
	global_load_dwordx4 v[80:83], v[8:9], off offset:128
	global_load_dwordx4 v[84:87], v[16:17], off offset:192
	global_load_dwordx4 v[88:91], v[10:11], off offset:192
	global_load_dwordx4 v[92:95], v[34:35], off offset:192
	global_load_dwordx4 v[96:99], v[8:9], off offset:192
	s_waitcnt vmcnt(14)
	v_mfma_f32_16x16x32_bf16 v[4:7], v[40:43], v[36:39], 0
	s_waitcnt vmcnt(12)
	v_mfma_f32_16x16x32_bf16 v[22:25], v[48:51], v[36:39], 0
	s_waitcnt vmcnt(12)
	v_mfma_f32_16x16x32_bf16 v[0:3], v[44:47], v[36:39], 0
	s_waitcnt vmcnt(10)
	v_mfma_f32_16x16x32_bf16 v[4:7], v[56:59], v[52:55], v[4:7]
	s_waitcnt vmcnt(9)
	v_mfma_f32_16x16x32_bf16 v[22:25], v[60:63], v[52:55], v[22:25]
	s_waitcnt vmcnt(8)
	v_mfma_f32_16x16x32_bf16 v[0:3], v[64:67], v[52:55], v[0:3]
	s_waitcnt vmcnt(6)
	v_mfma_f32_16x16x32_bf16 v[4:7], v[72:75], v[68:71], v[4:7]
	s_waitcnt vmcnt(5)
	v_mfma_f32_16x16x32_bf16 v[22:25], v[76:79], v[68:71], v[22:25]
	s_waitcnt vmcnt(4)
	v_mfma_f32_16x16x32_bf16 v[0:3], v[80:83], v[68:71], v[0:3]
	s_waitcnt vmcnt(2)
	v_mfma_f32_16x16x32_bf16 v[4:7], v[88:91], v[84:87], v[4:7]
	s_waitcnt vmcnt(1)
	v_mfma_f32_16x16x32_bf16 v[22:25], v[92:95], v[84:87], v[22:25]
	s_waitcnt vmcnt(0)
	v_mfma_f32_16x16x32_bf16 v[0:3], v[96:99], v[84:87], v[0:3]
	global_load_dwordx4 v[36:39], v[16:17], off offset:256
	global_load_dwordx4 v[40:43], v[10:11], off offset:256
	global_load_dwordx4 v[44:47], v[34:35], off offset:256
	global_load_dwordx4 v[48:51], v[8:9], off offset:256
	global_load_dwordx4 v[52:55], v[16:17], off offset:320
	global_load_dwordx4 v[56:59], v[10:11], off offset:320
	global_load_dwordx4 v[60:63], v[34:35], off offset:320
	global_load_dwordx4 v[64:67], v[8:9], off offset:320
	global_load_dwordx4 v[68:71], v[16:17], off offset:384
	global_load_dwordx4 v[72:75], v[10:11], off offset:384
	global_load_dwordx4 v[76:79], v[34:35], off offset:384
	global_load_dwordx4 v[80:83], v[8:9], off offset:384
	global_load_dwordx4 v[84:87], v[16:17], off offset:448
	global_load_dwordx4 v[88:91], v[10:11], off offset:448
	global_load_dwordx4 v[92:95], v[8:9], off offset:448
	global_load_dwordx4 v[96:99], v[34:35], off offset:448
	s_waitcnt vmcnt(14)
	v_mfma_f32_16x16x32_bf16 v[4:7], v[40:43], v[36:39], v[4:7]
	s_waitcnt vmcnt(13)
	v_mfma_f32_16x16x32_bf16 v[22:25], v[44:47], v[36:39], v[22:25]
	s_waitcnt vmcnt(12)
	v_mfma_f32_16x16x32_bf16 v[0:3], v[48:51], v[36:39], v[0:3]
	s_waitcnt vmcnt(10)
	v_mfma_f32_16x16x32_bf16 v[4:7], v[56:59], v[52:55], v[4:7]
	s_waitcnt vmcnt(9)
	v_mfma_f32_16x16x32_bf16 v[22:25], v[60:63], v[52:55], v[22:25]
	s_waitcnt vmcnt(8)
	v_mfma_f32_16x16x32_bf16 v[0:3], v[64:67], v[52:55], v[0:3]
	s_waitcnt vmcnt(6)
	v_mfma_f32_16x16x32_bf16 v[4:7], v[72:75], v[68:71], v[4:7]
	s_waitcnt vmcnt(5)
	v_mfma_f32_16x16x32_bf16 v[22:25], v[76:79], v[68:71], v[22:25]
	s_waitcnt vmcnt(4)
	v_mfma_f32_16x16x32_bf16 v[26:29], v[80:83], v[68:71], v[0:3]
	s_waitcnt vmcnt(2)
	v_mfma_f32_16x16x32_bf16 v[0:3], v[88:91], v[84:87], v[4:7]
	s_waitcnt vmcnt(0)
	v_mfma_f32_16x16x32_bf16 v[4:7], v[96:99], v[84:87], v[22:25]
	s_waitcnt vmcnt(0)
	v_mfma_f32_16x16x32_bf16 v[8:11], v[92:95], v[84:87], v[26:29]
	s_nop 7
	s_nop 0
	ds_write_b128 v21, v[0:3]
	s_nop 4
	ds_write_b128 v21, v[4:7] offset:1024
	ds_write_b128 v21, v[8:11] offset:2048
	v_cndmask_b32_e64 v21, 0, 1, s[12:13]
	v_cmp_ne_u32_e64 s[2:3], 1, v21
	s_waitcnt lgkmcnt(0)
	s_barrier
; template <int NACC> __device__ __forceinline__ void meta_tile(const bf16* A, int K, const bf16* B0, const bf16* B1, const bf16* B2, LAS float* red, int wid, int lane, f32x4 (&out)[NACC]) {
;     ...
;     __syncthreads();
;     if (wid == 0) {
; #pragma unroll
;         for (int j = 0; j < NACC; ++j) { f32x4 s = R[j * 64 + lane];
; #pragma unroll
;             for (int w = 1; w < 8; ++w) s += R[(w * NACC + j) * 64 + lane];
;             out[j] = s; }
	s_cbranch_vccnz .LBB0_434
	ds_read_b128 v[0:3], v20
	ds_read_b128 v[4:7], v20 offset:3072
	s_waitcnt lgkmcnt(0)
	v_pk_add_f32 v[6:7], v[2:3], v[6:7]
	v_pk_add_f32 v[4:5], v[0:1], v[4:5]
	ds_read_b128 v[0:3], v20 offset:6144
	s_waitcnt lgkmcnt(0)
	v_pk_add_f32 v[6:7], v[6:7], v[2:3]
	v_pk_add_f32 v[4:5], v[4:5], v[0:1]
	ds_read_b128 v[0:3], v20 offset:9216
	s_waitcnt lgkmcnt(0)
	v_pk_add_f32 v[6:7], v[6:7], v[2:3]
	v_pk_add_f32 v[4:5], v[4:5], v[0:1]
	ds_read_b128 v[0:3], v20 offset:12288
	s_waitcnt lgkmcnt(0)
	v_pk_add_f32 v[6:7], v[6:7], v[2:3]
	v_pk_add_f32 v[4:5], v[4:5], v[0:1]
	ds_read_b128 v[0:3], v20 offset:15360
	s_waitcnt lgkmcnt(0)
	v_pk_add_f32 v[6:7], v[6:7], v[2:3]
	v_pk_add_f32 v[4:5], v[4:5], v[0:1]
	ds_read_b128 v[0:3], v20 offset:18432
	s_waitcnt lgkmcnt(0)
	v_pk_add_f32 v[6:7], v[6:7], v[2:3]
	v_pk_add_f32 v[4:5], v[4:5], v[0:1]
	ds_read_b128 v[0:3], v20 offset:21504
	s_waitcnt lgkmcnt(0)
	v_pk_add_f32 v[2:3], v[6:7], v[2:3]
	v_pk_add_f32 v[0:1], v[4:5], v[0:1]
	ds_read_b128 v[4:7], v20 offset:1024
	ds_read_b128 v[8:11], v20 offset:4096
	s_waitcnt lgkmcnt(0)
	v_pk_add_f32 v[10:11], v[6:7], v[10:11]
	v_pk_add_f32 v[8:9], v[4:5], v[8:9]
	ds_read_b128 v[4:7], v20 offset:7168
	s_waitcnt lgkmcnt(0)
	v_pk_add_f32 v[10:11], v[10:11], v[6:7]
	v_pk_add_f32 v[8:9], v[8:9], v[4:5]
	ds_read_b128 v[4:7], v20 offset:10240
	s_waitcnt lgkmcnt(0)
	v_pk_add_f32 v[10:11], v[10:11], v[6:7]
	v_pk_add_f32 v[8:9], v[8:9], v[4:5]
	ds_read_b128 v[4:7], v20 offset:13312
	s_waitcnt lgkmcnt(0)
	v_pk_add_f32 v[10:11], v[10:11], v[6:7]
	v_pk_add_f32 v[8:9], v[8:9], v[4:5]
	ds_read_b128 v[4:7], v20 offset:16384
	s_waitcnt lgkmcnt(0)
	v_pk_add_f32 v[10:11], v[10:11], v[6:7]
	v_pk_add_f32 v[8:9], v[8:9], v[4:5]
	ds_read_b128 v[4:7], v20 offset:19456
	s_waitcnt lgkmcnt(0)
	v_pk_add_f32 v[10:11], v[10:11], v[6:7]
	v_pk_add_f32 v[8:9], v[8:9], v[4:5]
	ds_read_b128 v[4:7], v20 offset:22528
	s_waitcnt lgkmcnt(0)
	v_pk_add_f32 v[6:7], v[10:11], v[6:7]
	v_pk_add_f32 v[4:5], v[8:9], v[4:5]
	ds_read_b128 v[8:11], v20 offset:2048
	ds_read_b128 v[22:25], v20 offset:5120
	s_waitcnt lgkmcnt(0)
	v_pk_add_f32 v[24:25], v[10:11], v[24:25]
	v_pk_add_f32 v[22:23], v[8:9], v[22:23]
	ds_read_b128 v[8:11], v20 offset:8192
	s_waitcnt lgkmcnt(0)
	v_pk_add_f32 v[24:25], v[24:25], v[10:11]
	v_pk_add_f32 v[22:23], v[22:23], v[8:9]
	ds_read_b128 v[8:11], v20 offset:11264
	s_waitcnt lgkmcnt(0)
	v_pk_add_f32 v[24:25], v[24:25], v[10:11]
	v_pk_add_f32 v[22:23], v[22:23], v[8:9]
	ds_read_b128 v[8:11], v20 offset:14336
	s_waitcnt lgkmcnt(0)
	v_pk_add_f32 v[24:25], v[24:25], v[10:11]
	v_pk_add_f32 v[22:23], v[22:23], v[8:9]
	ds_read_b128 v[8:11], v20 offset:17408
	s_waitcnt lgkmcnt(0)
	v_pk_add_f32 v[24:25], v[24:25], v[10:11]
	v_pk_add_f32 v[22:23], v[22:23], v[8:9]
	ds_read_b128 v[8:11], v20 offset:20480
	s_waitcnt lgkmcnt(0)
	v_pk_add_f32 v[24:25], v[24:25], v[10:11]
	v_pk_add_f32 v[22:23], v[22:23], v[8:9]
	ds_read_b128 v[8:11], v20 offset:23552
	s_waitcnt lgkmcnt(0)
	v_pk_add_f32 v[10:11], v[24:25], v[10:11]
	v_pk_add_f32 v[8:9], v[22:23], v[8:9]

; #define LAS __attribute__((address_space(3)))
; template <int NACC> __device__ __forceinline__ void meta_tile(const bf16* A, int K, const bf16* B0, const bf16* B1, const bf16* B2, LAS float* red, int wid, int lane, f32x4 (&out)[NACC]) {
;     const int ks = K >> 3, r = lane & 15, kq = (lane >> 4) * 8;
;     const size_t off = (size_t)r * K + wid * ks + kq;
;     const bf16* ap = A + off; const bf16* bp[3] = {B0 + off, B1 + off, B2 + off};
;     f32x4 acc[NACC];
; #pragma unroll
;     for (int j = 0; j < NACC; ++j) acc[j] = (f32x4){0.f, 0.f, 0.f, 0.f};
; #pragma unroll 8
;     for (int k = 0; k < ks; k += 32) {
;         const bf16x8 a = *(const bf16x8*)(ap + k);
; #pragma unroll
;         for (int j = 0; j < NACC; ++j) { const bf16x8 b = *(const bf16x8*)(bp[j] + k); acc[j] = __builtin_amdgcn_mfma_f32_16x16x32_bf16(b, a, acc[j], 0, 0, 0); }
;     }
;     LAS f32x4* R = (LAS f32x4*)red;
; #pragma unroll
;     for (int j = 0; j < NACC; ++j) { R[(wid * NACC + j) * 64 + lane] = acc[j]; out[j] = acc[j]; }
;     __syncthreads();
;     if (wid == 0) {
; #pragma unroll
;         for (int j = 0; j < NACC; ++j) { f32x4 s = R[j * 64 + lane];
; #pragma unroll
;             for (int w = 1; w < 8; ++w) s += R[(w * NACC + j) * 64 + lane];
;             out[j] = s; }
; __global__ void __launch_bounds__(512, 2) fwd_mega(Args args) {
;     ...
;                 for (int nt = bx; nt < 128; nt += G) {
;                     f32x4 r1[1];
;                     meta_tile<1>(Zm, DM, W2 + (size_t)(16 * nt) * DM, W2, W2, red, wid, lane, r1);
.LBB0_643:
	s_ashr_i32 s1, s0, 31
	s_lshl_b64 s[4:5], s[0:1], 12
	v_lshl_add_u64 v[20:21], v[6:7], 0, s[4:5]
	s_waitcnt lgkmcnt(0)
	global_load_dwordx4 v[24:27], v[4:5], off
	global_load_dwordx4 v[28:31], v[20:21], off
	v_add_u32_e32 v11, s12, v10
	s_andn2_b64 vcc, exec, s[6:7]
	global_load_dwordx4 v[32:35], v[4:5], off offset:64
	global_load_dwordx4 v[36:39], v[20:21], off offset:64
	global_load_dwordx4 v[40:43], v[4:5], off offset:128
	global_load_dwordx4 v[44:47], v[20:21], off offset:128
	global_load_dwordx4 v[48:51], v[4:5], off offset:192
	global_load_dwordx4 v[52:55], v[20:21], off offset:192
	global_load_dwordx4 v[56:59], v[4:5], off offset:256
	global_load_dwordx4 v[60:63], v[20:21], off offset:256
	global_load_dwordx4 v[64:67], v[4:5], off offset:320
	global_load_dwordx4 v[68:71], v[20:21], off offset:320
	global_load_dwordx4 v[72:75], v[4:5], off offset:384
	global_load_dwordx4 v[76:79], v[20:21], off offset:384
	global_load_dwordx4 v[80:83], v[4:5], off offset:448
	global_load_dwordx4 v[84:87], v[20:21], off offset:448
	s_waitcnt vmcnt(14)
	v_mfma_f32_16x16x32_bf16 v[0:3], v[28:31], v[24:27], 0
	s_waitcnt vmcnt(12)
	v_mfma_f32_16x16x32_bf16 v[0:3], v[36:39], v[32:35], v[0:3]
	s_waitcnt vmcnt(10)
	v_mfma_f32_16x16x32_bf16 v[0:3], v[44:47], v[40:43], v[0:3]
	s_waitcnt vmcnt(8)
	v_mfma_f32_16x16x32_bf16 v[0:3], v[52:55], v[48:51], v[0:3]
	s_waitcnt vmcnt(6)
	v_mfma_f32_16x16x32_bf16 v[0:3], v[60:63], v[56:59], v[0:3]
	s_waitcnt vmcnt(4)
	v_mfma_f32_16x16x32_bf16 v[0:3], v[68:71], v[64:67], v[0:3]
	s_waitcnt vmcnt(2)
	v_mfma_f32_16x16x32_bf16 v[0:3], v[76:79], v[72:75], v[0:3]
	s_waitcnt vmcnt(0)
	v_mfma_f32_16x16x32_bf16 v[0:3], v[84:87], v[80:83], v[0:3]
	s_nop 7
	s_nop 7
	ds_write_b128 v11, v[0:3]
	v_cndmask_b32_e64 v11, 0, 1, s[6:7]
	v_cmp_ne_u32_e64 s[4:5], 1, v11
	s_waitcnt lgkmcnt(0)
	s_barrier
	s_cbranch_vccnz .LBB0_645
	ds_read_b128 v[0:3], v10
	ds_read_b128 v[12:15], v10 offset:1024
	s_waitcnt lgkmcnt(0)
	v_pk_add_f32 v[14:15], v[2:3], v[14:15]
	v_pk_add_f32 v[12:13], v[0:1], v[12:13]
	ds_read_b128 v[0:3], v10 offset:2048
	s_waitcnt lgkmcnt(0)
	v_pk_add_f32 v[14:15], v[14:15], v[2:3]
	v_pk_add_f32 v[12:13], v[12:13], v[0:1]
	ds_read_b128 v[0:3], v10 offset:3072
	s_waitcnt lgkmcnt(0)
	v_pk_add_f32 v[14:15], v[14:15], v[2:3]
	v_pk_add_f32 v[12:13], v[12:13], v[0:1]
	ds_read_b128 v[0:3], v10 offset:4096
	s_waitcnt lgkmcnt(0)
	v_pk_add_f32 v[14:15], v[14:15], v[2:3]
	v_pk_add_f32 v[12:13], v[12:13], v[0:1]
	ds_read_b128 v[0:3], v10 offset:5120
	s_waitcnt lgkmcnt(0)
	v_pk_add_f32 v[14:15], v[14:15], v[2:3]
	v_pk_add_f32 v[12:13], v[12:13], v[0:1]
	ds_read_b128 v[0:3], v10 offset:6144
	s_waitcnt lgkmcnt(0)
	v_pk_add_f32 v[14:15], v[14:15], v[2:3]
	v_pk_add_f32 v[12:13], v[12:13], v[0:1]
	ds_read_b128 v[0:3], v10 offset:7168
	s_waitcnt lgkmcnt(0)
	v_pk_add_f32 v[2:3], v[14:15], v[2:3]
	v_pk_add_f32 v[0:1], v[12:13], v[0:1]

; #define LAS __attribute__((address_space(3)))
; template <int NACC> __device__ __forceinline__ void meta_tile(const bf16* A, int K, const bf16* B0, const bf16* B1, const bf16* B2, LAS float* red, int wid, int lane, f32x4 (&out)[NACC]) {
;     const int ks = K >> 3, r = lane & 15, kq = (lane >> 4) * 8;
;     const size_t off = (size_t)r * K + wid * ks + kq;
;     const bf16* ap = A + off; const bf16* bp[3] = {B0 + off, B1 + off, B2 + off};
;     f32x4 acc[NACC];
; #pragma unroll
;     for (int j = 0; j < NACC; ++j) acc[j] = (f32x4){0.f, 0.f, 0.f, 0.f};
; #pragma unroll 8
;     for (int k = 0; k < ks; k += 32) {
;         const bf16x8 a = *(const bf16x8*)(ap + k);
; #pragma unroll
;         for (int j = 0; j < NACC; ++j) { const bf16x8 b = *(const bf16x8*)(bp[j] + k); acc[j] = __builtin_amdgcn_mfma_f32_16x16x32_bf16(b, a, acc[j], 0, 0, 0); }
;     }
;     LAS f32x4* R = (LAS f32x4*)red;
; #pragma unroll
;     for (int j = 0; j < NACC; ++j) { R[(wid * NACC + j) * 64 + lane] = acc[j]; out[j] = acc[j]; }
;     __syncthreads();
;     if (wid == 0) {
; #pragma unroll
;         for (int j = 0; j < NACC; ++j) { f32x4 s = R[j * 64 + lane];
; #pragma unroll
;             for (int w = 1; w < 8; ++w) s += R[(w * NACC + j) * 64 + lane];
;             out[j] = s; }
;     }
;     __syncthreads();
; }
.LBB0_724:
	s_ashr_i32 s7, s6, 31
	s_lshl_b64 s[0:1], s[6:7], 12
	s_add_u32 s0, s49, s0
	s_addc_u32 s1, s50, s1
	v_lshl_add_u64 v[26:27], v[8:9], 1, s[0:1]
	v_add_co_u32_e32 v18, vcc, s78, v26
	global_load_dwordx4 v[32:35], v[10:11], off
	global_load_dwordx4 v[36:39], v[26:27], off
	v_addc_co_u32_e32 v19, vcc, 0, v27, vcc
	global_load_dwordx4 v[40:43], v[18:19], off
	s_mov_b64 s[0:1], 0x10000
	v_lshl_add_u64 v[28:29], v[26:27], 0, s[0:1]
	v_add_u32_e32 v16, s8, v17
	s_andn2_b64 vcc, exec, s[4:5]
	global_load_dwordx4 v[44:47], v[10:11], off offset:64
	global_load_dwordx4 v[48:51], v[26:27], off offset:64
	global_load_dwordx4 v[52:55], v[28:29], off offset:64
	global_load_dwordx4 v[56:59], v[10:11], off offset:128
	global_load_dwordx4 v[60:63], v[26:27], off offset:128
	global_load_dwordx4 v[64:67], v[28:29], off offset:128
	global_load_dwordx4 v[68:71], v[10:11], off offset:192
	global_load_dwordx4 v[72:75], v[26:27], off offset:192
	global_load_dwordx4 v[76:79], v[28:29], off offset:192
	global_load_dwordx4 v[80:83], v[10:11], off offset:256
	global_load_dwordx4 v[84:87], v[26:27], off offset:256
	global_load_dwordx4 v[88:91], v[28:29], off offset:256
	global_load_dwordx4 v[92:95], v[10:11], off offset:320
	global_load_dwordx4 v[96:99], v[26:27], off offset:320
	global_load_dwordx4 v[100:103], v[28:29], off offset:320
	global_load_dwordx4 v[104:107], v[10:11], off offset:384
	global_load_dwordx4 v[108:111], v[26:27], off offset:384
	global_load_dwordx4 v[112:115], v[28:29], off offset:384
	global_load_dwordx4 v[116:119], v[10:11], off offset:448
	global_load_dwordx4 v[120:123], v[26:27], off offset:448
	global_load_dwordx4 v[124:127], v[28:29], off offset:448
	s_waitcnt vmcnt(22)
	v_mfma_f32_16x16x32_bf16 v[4:7], v[36:39], v[32:35], 0
	s_waitcnt vmcnt(21)
	v_mfma_f32_16x16x32_bf16 v[0:3], v[40:43], v[32:35], 0
	s_waitcnt vmcnt(19)
	v_mfma_f32_16x16x32_bf16 v[4:7], v[48:51], v[44:47], v[4:7]
	s_waitcnt vmcnt(18)
	v_mfma_f32_16x16x32_bf16 v[0:3], v[52:55], v[44:47], v[0:3]
	s_waitcnt vmcnt(16)
	v_mfma_f32_16x16x32_bf16 v[4:7], v[60:63], v[56:59], v[4:7]
	s_waitcnt vmcnt(15)
	v_mfma_f32_16x16x32_bf16 v[0:3], v[64:67], v[56:59], v[0:3]
	s_waitcnt vmcnt(13)
	v_mfma_f32_16x16x32_bf16 v[4:7], v[72:75], v[68:71], v[4:7]
	s_waitcnt vmcnt(12)
	v_mfma_f32_16x16x32_bf16 v[0:3], v[76:79], v[68:71], v[0:3]
	s_waitcnt vmcnt(10)
	v_mfma_f32_16x16x32_bf16 v[4:7], v[84:87], v[80:83], v[4:7]
	s_waitcnt vmcnt(9)
	v_mfma_f32_16x16x32_bf16 v[0:3], v[88:91], v[80:83], v[0:3]
	s_waitcnt vmcnt(7)
	v_mfma_f32_16x16x32_bf16 v[4:7], v[96:99], v[92:95], v[4:7]
	s_waitcnt vmcnt(6)
	v_mfma_f32_16x16x32_bf16 v[0:3], v[100:103], v[92:95], v[0:3]
	s_waitcnt vmcnt(4)
	v_mfma_f32_16x16x32_bf16 v[4:7], v[108:111], v[104:107], v[4:7]
	s_waitcnt vmcnt(3)
	v_mfma_f32_16x16x32_bf16 v[18:21], v[112:115], v[104:107], v[0:3]
	s_waitcnt vmcnt(1)
	v_mfma_f32_16x16x32_bf16 v[0:3], v[120:123], v[116:119], v[4:7]
	s_waitcnt vmcnt(0)
	v_mfma_f32_16x16x32_bf16 v[4:7], v[124:127], v[116:119], v[18:21]
	s_nop 7
	s_nop 1
	ds_write_b128 v16, v[0:3]
	s_nop 4
	ds_write_b128 v16, v[4:7] offset:1024
	v_cndmask_b32_e64 v16, 0, 1, s[4:5]
	v_cmp_ne_u32_e64 s[2:3], 1, v16
	s_waitcnt lgkmcnt(0)
	s_barrier
	s_cbranch_vccnz .LBB0_726
	ds_read_b128 v[0:3], v17
	ds_read_b128 v[4:7], v17 offset:2048
	s_waitcnt lgkmcnt(0)
	v_pk_add_f32 v[6:7], v[2:3], v[6:7]
	v_pk_add_f32 v[4:5], v[0:1], v[4:5]
	ds_read_b128 v[0:3], v17 offset:4096
	s_waitcnt lgkmcnt(0)
	v_pk_add_f32 v[6:7], v[6:7], v[2:3]
	v_pk_add_f32 v[4:5], v[4:5], v[0:1]
	ds_read_b128 v[0:3], v17 offset:6144
	s_waitcnt lgkmcnt(0)
	v_pk_add_f32 v[6:7], v[6:7], v[2:3]
	v_pk_add_f32 v[4:5], v[4:5], v[0:1]
	ds_read_b128 v[0:3], v17 offset:8192
	s_waitcnt lgkmcnt(0)
	v_pk_add_f32 v[6:7], v[6:7], v[2:3]
	v_pk_add_f32 v[4:5], v[4:5], v[0:1]
	ds_read_b128 v[0:3], v17 offset:10240
	s_waitcnt lgkmcnt(0)
	v_pk_add_f32 v[6:7], v[6:7], v[2:3]
	v_pk_add_f32 v[4:5], v[4:5], v[0:1]
	ds_read_b128 v[0:3], v17 offset:12288
	s_waitcnt lgkmcnt(0)
	v_pk_add_f32 v[6:7], v[6:7], v[2:3]
	v_pk_add_f32 v[4:5], v[4:5], v[0:1]
	ds_read_b128 v[0:3], v17 offset:14336
	s_waitcnt lgkmcnt(0)
	v_pk_add_f32 v[2:3], v[6:7], v[2:3]
	v_pk_add_f32 v[0:1], v[4:5], v[0:1]
	ds_read_b128 v[4:7], v17 offset:1024
	ds_read_b128 v[18:21], v17 offset:3072
	s_waitcnt lgkmcnt(0)
	v_pk_add_f32 v[20:21], v[6:7], v[20:21]
	v_pk_add_f32 v[18:19], v[4:5], v[18:19]
	ds_read_b128 v[4:7], v17 offset:5120
	s_waitcnt lgkmcnt(0)
	v_pk_add_f32 v[20:21], v[20:21], v[6:7]
	v_pk_add_f32 v[18:19], v[18:19], v[4:5]
	ds_read_b128 v[4:7], v17 offset:7168
	s_waitcnt lgkmcnt(0)
	v_pk_add_f32 v[20:21], v[20:21], v[6:7]
	v_pk_add_f32 v[18:19], v[18:19], v[4:5]
	ds_read_b128 v[4:7], v17 offset:9216
	s_waitcnt lgkmcnt(0)
	v_pk_add_f32 v[20:21], v[20:21], v[6:7]
	v_pk_add_f32 v[18:19], v[18:19], v[4:5]
	ds_read_b128 v[4:7], v17 offset:11264
	s_waitcnt lgkmcnt(0)
	v_pk_add_f32 v[20:21], v[20:21], v[6:7]
	v_pk_add_f32 v[18:19], v[18:19], v[4:5]
	ds_read_b128 v[4:7], v17 offset:13312
	s_waitcnt lgkmcnt(0)
	v_pk_add_f32 v[20:21], v[20:21], v[6:7]
	v_pk_add_f32 v[18:19], v[18:19], v[4:5]
	ds_read_b128 v[4:7], v17 offset:15360
	s_waitcnt lgkmcnt(0)
	v_pk_add_f32 v[6:7], v[20:21], v[6:7]
	v_pk_add_f32 v[4:5], v[18:19], v[4:5]

; #define LAS __attribute__((address_space(3)))
; template <int NACC> __device__ __forceinline__ void meta_tile(const bf16* A, int K, const bf16* B0, const bf16* B1, const bf16* B2, LAS float* red, int wid, int lane, f32x4 (&out)[NACC]) {
;     const int ks = K >> 3, r = lane & 15, kq = (lane >> 4) * 8;
;     const size_t off = (size_t)r * K + wid * ks + kq;
;     const bf16* ap = A + off; const bf16* bp[3] = {B0 + off, B1 + off, B2 + off};
;     f32x4 acc[NACC];
; #pragma unroll
;     for (int j = 0; j < NACC; ++j) acc[j] = (f32x4){0.f, 0.f, 0.f, 0.f};
; #pragma unroll 8
;     for (int k = 0; k < ks; k += 32) {
;         const bf16x8 a = *(const bf16x8*)(ap + k);
; #pragma unroll
;         for (int j = 0; j < NACC; ++j) { const bf16x8 b = *(const bf16x8*)(bp[j] + k); acc[j] = __builtin_amdgcn_mfma_f32_16x16x32_bf16(b, a, acc[j], 0, 0, 0); }
;     }
;     LAS f32x4* R = (LAS f32x4*)red;
; #pragma unroll
;     for (int j = 0; j < NACC; ++j) { R[(wid * NACC + j) * 64 + lane] = acc[j]; out[j] = acc[j]; }
;     __syncthreads();
;     if (wid == 0) {
; #pragma unroll
;         for (int j = 0; j < NACC; ++j) { f32x4 s = R[j * 64 + lane];
; #pragma unroll
;             for (int w = 1; w < 8; ++w) s += R[(w * NACC + j) * 64 + lane];
;             out[j] = s; }
;     }
;     __syncthreads();
.LBB0_823:
	v_add_co_u32_e32 v20, vcc, 0x90000, v8
	v_lshl_add_u64 v[22:23], v[8:9], 0, s[0:1]
	s_nop 0
	v_addc_co_u32_e32 v21, vcc, 0, v9, vcc
	global_load_dwordx4 v[24:27], v[20:21], off
	global_load_dwordx4 v[28:31], v[22:23], off offset:-256
	s_addk_i32 s9, 0x100
	s_mov_b64 s[14:15], 0x200
	v_lshl_add_u64 v[8:9], v[8:9], 0, s[14:15]
	s_cmpk_gt_u32 s9, 0x3df
	global_load_dwordx4 v[32:35], v[20:21], off offset:64
	global_load_dwordx4 v[36:39], v[22:23], off offset:-192
	global_load_dwordx4 v[40:43], v[20:21], off offset:128
	global_load_dwordx4 v[44:47], v[22:23], off offset:-128
	global_load_dwordx4 v[48:51], v[20:21], off offset:192
	global_load_dwordx4 v[52:55], v[22:23], off offset:-64
	global_load_dwordx4 v[56:59], v[20:21], off offset:256
	global_load_dwordx4 v[60:63], v[22:23], off
	global_load_dwordx4 v[64:67], v[20:21], off offset:320
	global_load_dwordx4 v[68:71], v[22:23], off offset:64
	global_load_dwordx4 v[72:75], v[20:21], off offset:384
	global_load_dwordx4 v[76:79], v[22:23], off offset:128
	global_load_dwordx4 v[80:83], v[20:21], off offset:448
	global_load_dwordx4 v[84:87], v[22:23], off offset:192
	s_waitcnt vmcnt(14)
	v_mfma_f32_16x16x32_bf16 v[0:3], v[28:31], v[24:27], v[0:3]
	s_waitcnt vmcnt(12)
	v_mfma_f32_16x16x32_bf16 v[0:3], v[36:39], v[32:35], v[0:3]
	s_waitcnt vmcnt(10)
	v_mfma_f32_16x16x32_bf16 v[0:3], v[44:47], v[40:43], v[0:3]
	s_waitcnt vmcnt(8)
	v_mfma_f32_16x16x32_bf16 v[0:3], v[52:55], v[48:51], v[0:3]
	s_waitcnt vmcnt(6)
	v_mfma_f32_16x16x32_bf16 v[0:3], v[60:63], v[56:59], v[0:3]
	s_waitcnt vmcnt(4)
	v_mfma_f32_16x16x32_bf16 v[0:3], v[68:71], v[64:67], v[0:3]
	s_waitcnt vmcnt(2)
	v_mfma_f32_16x16x32_bf16 v[0:3], v[76:79], v[72:75], v[0:3]
	s_waitcnt vmcnt(0)
	v_mfma_f32_16x16x32_bf16 v[0:3], v[84:87], v[80:83], v[0:3]
	s_nop 7
	s_cbranch_scc0 .LBB0_823
	v_add_u32_e32 v8, s8, v10
	s_and_b64 vcc, exec, s[10:11]
	s_nop 4
	ds_write_b128 v8, v[0:3]
	s_waitcnt lgkmcnt(0)
	s_barrier
	s_cbranch_vccz .LBB0_826
	ds_read_b128 v[0:3], v10
	ds_read_b128 v[12:15], v10 offset:1024
	s_waitcnt lgkmcnt(0)
	v_pk_add_f32 v[8:9], v[2:3], v[14:15]
	v_pk_add_f32 v[12:13], v[0:1], v[12:13]
	ds_read_b128 v[0:3], v10 offset:2048
	s_waitcnt lgkmcnt(0)
	v_pk_add_f32 v[8:9], v[8:9], v[2:3]
	v_pk_add_f32 v[12:13], v[12:13], v[0:1]
	ds_read_b128 v[0:3], v10 offset:3072
	s_waitcnt lgkmcnt(0)
	v_pk_add_f32 v[8:9], v[8:9], v[2:3]
	v_pk_add_f32 v[12:13], v[12:13], v[0:1]
	ds_read_b128 v[0:3], v10 offset:4096
	s_waitcnt lgkmcnt(0)
	v_pk_add_f32 v[8:9], v[8:9], v[2:3]
	v_pk_add_f32 v[12:13], v[12:13], v[0:1]
	ds_read_b128 v[0:3], v10 offset:5120
	s_waitcnt lgkmcnt(0)
	v_pk_add_f32 v[8:9], v[8:9], v[2:3]
	v_pk_add_f32 v[12:13], v[12:13], v[0:1]
	ds_read_b128 v[0:3], v10 offset:6144
	s_waitcnt lgkmcnt(0)
	v_pk_add_f32 v[8:9], v[8:9], v[2:3]
	v_pk_add_f32 v[12:13], v[12:13], v[0:1]
	ds_read_b128 v[0:3], v10 offset:7168
	s_waitcnt lgkmcnt(0)
	v_pk_add_f32 v[2:3], v[8:9], v[2:3]
	v_pk_add_f32 v[0:1], v[12:13], v[0:1]
